# deep 2-K-step LDS-DMA pipeline (counted vmcnt) in od_win, ev_win, wout K-loops
# speedup vs baseline: 1.0295x; 1.0295x over previous
.LBB0_508:
	v_cmp_gt_i32_e32 vcc, s2, v117
	s_mov_b64 s[0:1], 0x80
	v_lshl_add_u64 v[104:105], v[66:67], 0, s[0:1]
	v_cndmask_b32_e32 v0, 0, v199, vcc
	v_cmp_gt_i32_e32 vcc, s2, v119
	v_mov_b32_e32 v3, v1
	v_mov_b32_e32 v5, v1
	v_cndmask_b32_e32 v2, 0, v206, vcc
	v_cmp_gt_i32_e32 vcc, s2, v121
	v_mov_b32_e32 v42, 0
	s_mov_b32 s4, 0
	v_cndmask_b32_e32 v4, 0, v207, vcc
	v_lshl_add_u64 v[106:107], v[104:105], 0, v[0:1]
	v_lshl_add_u64 v[108:109], v[104:105], 0, v[2:3]
	v_lshl_add_u64 v[110:111], v[104:105], 0, v[4:5]
	s_mov_b64 s[0:1], 0
	v_readfirstlane_b32 s60, v98
	v_readfirstlane_b32 s61, v99
	v_readfirstlane_b32 s62, v104
	v_readfirstlane_b32 s63, v105
	v_readfirstlane_b32 s64, v112
	v_subrev_u32_e32 v140, s60, v98
	v_subrev_u32_e32 v144, s62, v104
	v_subrev_u32_e32 v145, s62, v106
	v_subrev_u32_e32 v146, s62, v108
	v_subrev_u32_e32 v147, s62, v110
	v_add_u32_e32 v141, 0x10000, v140
	v_add_u32_e32 v142, 0x20000, v140
	v_add_u32_e32 v143, 0x30000, v140
	v_add3_u32 v136, v124, v125, v126
	v_add3_u32 v137, v124, v127, v126
	v_add3_u32 v138, v123, v125, v126
	v_add3_u32 v139, v123, v127, v126
	s_add_u32 s60, s60, 0x80
	s_addc_u32 s61, s61, 0
	s_add_u32 m0, s64, 0x8000
	v_mov_b32_e32 v43, v42
	global_load_lds_dwordx4 v140, s[60:61]
	v_mov_b32_e32 v44, v42
	v_mov_b32_e32 v45, v42
	v_mov_b32_e32 v2, v42
	s_add_u32 m0, s64, 0x9000
	v_mov_b32_e32 v3, v42
	global_load_lds_dwordx4 v141, s[60:61]
	v_mov_b32_e32 v4, v42
	v_mov_b32_e32 v5, v42
	v_mov_b32_e32 v6, v42
	s_add_u32 m0, s64, 0xa000
	v_mov_b32_e32 v7, v42
	global_load_lds_dwordx4 v142, s[60:61]
	v_mov_b32_e32 v8, v42
	v_mov_b32_e32 v9, v42
	v_mov_b32_e32 v10, v42
	s_add_u32 m0, s64, 0xb000
	v_mov_b32_e32 v11, v42
	global_load_lds_dwordx4 v143, s[60:61]
	v_mov_b32_e32 v12, v42
	v_mov_b32_e32 v13, v42
	v_mov_b32_e32 v14, v42
	s_add_u32 m0, s64, 0xc000
	v_mov_b32_e32 v15, v42
	global_load_lds_dwordx4 v144, s[62:63]
	v_mov_b32_e32 v16, v42
	v_mov_b32_e32 v17, v42
	v_mov_b32_e32 v18, v42
	s_add_u32 m0, s64, 0xd000
	v_mov_b32_e32 v19, v42
	global_load_lds_dwordx4 v145, s[62:63]
	v_mov_b32_e32 v20, v42
	v_mov_b32_e32 v21, v42
	v_mov_b32_e32 v22, v42
	s_add_u32 m0, s64, 0xe000
	v_mov_b32_e32 v23, v42
	global_load_lds_dwordx4 v146, s[62:63]
	v_mov_b32_e32 v24, v42
	v_mov_b32_e32 v25, v42
	v_mov_b32_e32 v26, v42
	s_add_u32 m0, s64, 0xf000
	v_mov_b32_e32 v27, v42
	global_load_lds_dwordx4 v147, s[62:63]
	v_mov_b32_e32 v28, v42
	v_mov_b32_e32 v29, v42
	v_mov_b32_e32 v30, v42
	v_mov_b32_e32 v31, v42
	v_mov_b32_e32 v32, v42
	v_mov_b32_e32 v33, v42
	v_mov_b32_e32 v34, v42
	v_mov_b32_e32 v35, v42
	v_mov_b32_e32 v36, v42
	v_mov_b32_e32 v37, v42
	v_mov_b32_e32 v38, v42
	v_mov_b32_e32 v39, v42
	v_mov_b32_e32 v40, v42
	v_mov_b32_e32 v41, v42
	v_mov_b32_e32 v46, v42
	v_mov_b32_e32 v47, v42
	v_mov_b32_e32 v48, v42
	v_mov_b32_e32 v49, v42
	v_mov_b32_e32 v50, v42
	v_mov_b32_e32 v51, v42
	v_mov_b32_e32 v52, v42
	v_mov_b32_e32 v53, v42
	v_mov_b32_e32 v54, v42
	v_mov_b32_e32 v55, v42
	v_mov_b32_e32 v56, v42
	v_mov_b32_e32 v57, v42
	v_mov_b32_e32 v58, v42
	v_mov_b32_e32 v59, v42
	v_mov_b32_e32 v60, v42
	v_mov_b32_e32 v61, v42
	v_mov_b32_e32 v62, v42
	v_mov_b32_e32 v63, v42
	v_mov_b32_e32 v64, v42
	v_mov_b32_e32 v65, v42
	s_add_u32 s60, s60, 0x80
	s_addc_u32 s61, s61, 0
	s_add_u32 s62, s62, 0x80
	s_addc_u32 s63, s63, 0
	s_mov_b64 s[12:13], 0x10000
	s_mov_b64 s[14:15], 0x20000
	s_mov_b64 s[16:17], 0x30000
	s_mov_b64 s[8:9], 0x10080
	s_mov_b64 s[10:11], 0x20080
	s_mov_b64 s[18:19], 0x30080
	s_waitcnt vmcnt(8) lgkmcnt(0)
	s_barrier
	ds_read_b128 v[66:69], v136 offset:0
	ds_read_b128 v[82:85], v137 offset:16384
	ds_read_b128 v[86:89], v137 offset:18432
	ds_read_b128 v[70:73], v136 offset:2048
	ds_read_b128 v[90:93], v137 offset:20480
	ds_read_b128 v[94:97], v137 offset:22528
	ds_read_b128 v[74:77], v136 offset:4096
	ds_read_b128 v[78:81], v136 offset:6144
	s_mov_b32 s65, 7
.Levwin_loop:
	ds_read_b128 v[148:151], v138 offset:0
	ds_read_b128 v[172:175], v139 offset:16384
	ds_read_b128 v[176:179], v139 offset:18432
	ds_read_b128 v[152:155], v138 offset:2048
	ds_read_b128 v[180:183], v139 offset:20480
	ds_read_b128 v[184:187], v139 offset:22528
	ds_read_b128 v[156:159], v138 offset:4096
	ds_read_b128 v[168:171], v138 offset:6144
	s_waitcnt lgkmcnt(8)
	v_mfma_f32_16x16x32_bf16 v[62:65], v[66:69], v[82:85], v[62:65]
	v_mfma_f32_16x16x32_bf16 v[58:61], v[66:69], v[86:89], v[58:61]
	v_mfma_f32_16x16x32_bf16 v[54:57], v[66:69], v[90:93], v[54:57]
	v_mfma_f32_16x16x32_bf16 v[50:53], v[66:69], v[94:97], v[50:53]
	v_mfma_f32_16x16x32_bf16 v[46:49], v[70:73], v[82:85], v[46:49]
	v_mfma_f32_16x16x32_bf16 v[38:41], v[70:73], v[86:89], v[38:41]
	v_mfma_f32_16x16x32_bf16 v[34:37], v[70:73], v[90:93], v[34:37]
	v_mfma_f32_16x16x32_bf16 v[30:33], v[70:73], v[94:97], v[30:33]
	v_mfma_f32_16x16x32_bf16 v[26:29], v[74:77], v[82:85], v[26:29]
	v_mfma_f32_16x16x32_bf16 v[22:25], v[74:77], v[86:89], v[22:25]
	v_mfma_f32_16x16x32_bf16 v[18:21], v[74:77], v[90:93], v[18:21]
	v_mfma_f32_16x16x32_bf16 v[14:17], v[74:77], v[94:97], v[14:17]
	v_mfma_f32_16x16x32_bf16 v[10:13], v[78:81], v[82:85], v[10:13]
	v_mfma_f32_16x16x32_bf16 v[6:9], v[78:81], v[86:89], v[6:9]
	v_mfma_f32_16x16x32_bf16 v[2:5], v[78:81], v[90:93], v[2:5]
	v_mfma_f32_16x16x32_bf16 v[42:45], v[78:81], v[94:97], v[42:45]
	s_waitcnt lgkmcnt(0)
	s_barrier
	s_add_u32 m0, s64, 0x0
	v_mfma_f32_16x16x32_bf16 v[62:65], v[148:151], v[172:175], v[62:65]
	global_load_lds_dwordx4 v140, s[60:61]
	s_add_u32 m0, s64, 0x1000
	v_mfma_f32_16x16x32_bf16 v[58:61], v[148:151], v[176:179], v[58:61]
	global_load_lds_dwordx4 v141, s[60:61]
	s_add_u32 m0, s64, 0x2000
	v_mfma_f32_16x16x32_bf16 v[54:57], v[148:151], v[180:183], v[54:57]
	global_load_lds_dwordx4 v142, s[60:61]
	s_add_u32 m0, s64, 0x3000
	v_mfma_f32_16x16x32_bf16 v[50:53], v[148:151], v[184:187], v[50:53]
	global_load_lds_dwordx4 v143, s[60:61]
	s_add_u32 m0, s64, 0x4000
	v_mfma_f32_16x16x32_bf16 v[46:49], v[152:155], v[172:175], v[46:49]
	global_load_lds_dwordx4 v144, s[62:63]
	s_add_u32 m0, s64, 0x5000
	v_mfma_f32_16x16x32_bf16 v[38:41], v[152:155], v[176:179], v[38:41]
	global_load_lds_dwordx4 v145, s[62:63]
	s_add_u32 m0, s64, 0x6000
	v_mfma_f32_16x16x32_bf16 v[34:37], v[152:155], v[180:183], v[34:37]
	global_load_lds_dwordx4 v146, s[62:63]
	s_add_u32 m0, s64, 0x7000
	v_mfma_f32_16x16x32_bf16 v[30:33], v[152:155], v[184:187], v[30:33]
	global_load_lds_dwordx4 v147, s[62:63]
	s_add_u32 s60, s60, 0x80
	s_addc_u32 s61, s61, 0
	s_add_u32 s62, s62, 0x80
	s_addc_u32 s63, s63, 0
	s_waitcnt vmcnt(8)
	s_barrier
	ds_read_b128 v[66:69], v136 offset:32768
	ds_read_b128 v[82:85], v137 offset:49152
	ds_read_b128 v[86:89], v137 offset:51200
	ds_read_b128 v[70:73], v136 offset:34816
	ds_read_b128 v[90:93], v137 offset:53248
	ds_read_b128 v[94:97], v137 offset:55296
	ds_read_b128 v[74:77], v136 offset:36864
	ds_read_b128 v[78:81], v136 offset:38912
	v_mfma_f32_16x16x32_bf16 v[26:29], v[156:159], v[172:175], v[26:29]
	v_mfma_f32_16x16x32_bf16 v[22:25], v[156:159], v[176:179], v[22:25]
	v_mfma_f32_16x16x32_bf16 v[18:21], v[156:159], v[180:183], v[18:21]
	v_mfma_f32_16x16x32_bf16 v[14:17], v[156:159], v[184:187], v[14:17]
	v_mfma_f32_16x16x32_bf16 v[10:13], v[168:171], v[172:175], v[10:13]
	v_mfma_f32_16x16x32_bf16 v[6:9], v[168:171], v[176:179], v[6:9]
	v_mfma_f32_16x16x32_bf16 v[2:5], v[168:171], v[180:183], v[2:5]
	v_mfma_f32_16x16x32_bf16 v[42:45], v[168:171], v[184:187], v[42:45]
	ds_read_b128 v[148:151], v138 offset:32768
	ds_read_b128 v[172:175], v139 offset:49152
	ds_read_b128 v[176:179], v139 offset:51200
	ds_read_b128 v[152:155], v138 offset:34816
	ds_read_b128 v[180:183], v139 offset:53248
	ds_read_b128 v[184:187], v139 offset:55296
	ds_read_b128 v[156:159], v138 offset:36864
	ds_read_b128 v[168:171], v138 offset:38912
	s_waitcnt lgkmcnt(8)
	v_mfma_f32_16x16x32_bf16 v[62:65], v[66:69], v[82:85], v[62:65]
	v_mfma_f32_16x16x32_bf16 v[58:61], v[66:69], v[86:89], v[58:61]
	v_mfma_f32_16x16x32_bf16 v[54:57], v[66:69], v[90:93], v[54:57]
	v_mfma_f32_16x16x32_bf16 v[50:53], v[66:69], v[94:97], v[50:53]
	v_mfma_f32_16x16x32_bf16 v[46:49], v[70:73], v[82:85], v[46:49]
	v_mfma_f32_16x16x32_bf16 v[38:41], v[70:73], v[86:89], v[38:41]
	v_mfma_f32_16x16x32_bf16 v[34:37], v[70:73], v[90:93], v[34:37]
	v_mfma_f32_16x16x32_bf16 v[30:33], v[70:73], v[94:97], v[30:33]
	v_mfma_f32_16x16x32_bf16 v[26:29], v[74:77], v[82:85], v[26:29]
	v_mfma_f32_16x16x32_bf16 v[22:25], v[74:77], v[86:89], v[22:25]
	v_mfma_f32_16x16x32_bf16 v[18:21], v[74:77], v[90:93], v[18:21]
	v_mfma_f32_16x16x32_bf16 v[14:17], v[74:77], v[94:97], v[14:17]
	v_mfma_f32_16x16x32_bf16 v[10:13], v[78:81], v[82:85], v[10:13]
	v_mfma_f32_16x16x32_bf16 v[6:9], v[78:81], v[86:89], v[6:9]
	v_mfma_f32_16x16x32_bf16 v[2:5], v[78:81], v[90:93], v[2:5]
	v_mfma_f32_16x16x32_bf16 v[42:45], v[78:81], v[94:97], v[42:45]
	s_waitcnt lgkmcnt(0)
	s_barrier
	s_add_u32 m0, s64, 0x8000
	v_mfma_f32_16x16x32_bf16 v[62:65], v[148:151], v[172:175], v[62:65]
	global_load_lds_dwordx4 v140, s[60:61]
	s_add_u32 m0, s64, 0x9000
	v_mfma_f32_16x16x32_bf16 v[58:61], v[148:151], v[176:179], v[58:61]
	global_load_lds_dwordx4 v141, s[60:61]
	s_add_u32 m0, s64, 0xa000
	v_mfma_f32_16x16x32_bf16 v[54:57], v[148:151], v[180:183], v[54:57]
	global_load_lds_dwordx4 v142, s[60:61]
	s_add_u32 m0, s64, 0xb000
	v_mfma_f32_16x16x32_bf16 v[50:53], v[148:151], v[184:187], v[50:53]
	global_load_lds_dwordx4 v143, s[60:61]
	s_add_u32 m0, s64, 0xc000
	v_mfma_f32_16x16x32_bf16 v[46:49], v[152:155], v[172:175], v[46:49]
	global_load_lds_dwordx4 v144, s[62:63]
	s_add_u32 m0, s64, 0xd000
	v_mfma_f32_16x16x32_bf16 v[38:41], v[152:155], v[176:179], v[38:41]
	global_load_lds_dwordx4 v145, s[62:63]
	s_add_u32 m0, s64, 0xe000
	v_mfma_f32_16x16x32_bf16 v[34:37], v[152:155], v[180:183], v[34:37]
	global_load_lds_dwordx4 v146, s[62:63]
	s_add_u32 m0, s64, 0xf000
	v_mfma_f32_16x16x32_bf16 v[30:33], v[152:155], v[184:187], v[30:33]
	global_load_lds_dwordx4 v147, s[62:63]
	s_add_u32 s60, s60, 0x80
	s_addc_u32 s61, s61, 0
	s_add_u32 s62, s62, 0x80
	s_addc_u32 s63, s63, 0
	s_waitcnt vmcnt(8)
	s_barrier
	ds_read_b128 v[66:69], v136 offset:0
	ds_read_b128 v[82:85], v137 offset:16384
	ds_read_b128 v[86:89], v137 offset:18432
	ds_read_b128 v[70:73], v136 offset:2048
	ds_read_b128 v[90:93], v137 offset:20480
	ds_read_b128 v[94:97], v137 offset:22528
	ds_read_b128 v[74:77], v136 offset:4096
	ds_read_b128 v[78:81], v136 offset:6144
	v_mfma_f32_16x16x32_bf16 v[26:29], v[156:159], v[172:175], v[26:29]
	v_mfma_f32_16x16x32_bf16 v[22:25], v[156:159], v[176:179], v[22:25]
	v_mfma_f32_16x16x32_bf16 v[18:21], v[156:159], v[180:183], v[18:21]
	v_mfma_f32_16x16x32_bf16 v[14:17], v[156:159], v[184:187], v[14:17]
	v_mfma_f32_16x16x32_bf16 v[10:13], v[168:171], v[172:175], v[10:13]
	v_mfma_f32_16x16x32_bf16 v[6:9], v[168:171], v[176:179], v[6:9]
	v_mfma_f32_16x16x32_bf16 v[2:5], v[168:171], v[180:183], v[2:5]
	v_mfma_f32_16x16x32_bf16 v[42:45], v[168:171], v[184:187], v[42:45]
	s_sub_i32 s65, s65, 1
	s_cmp_lg_u32 s65, 0
	s_cbranch_scc1 .Levwin_loop
	ds_read_b128 v[148:151], v138 offset:0
	ds_read_b128 v[172:175], v139 offset:16384
	ds_read_b128 v[176:179], v139 offset:18432
	ds_read_b128 v[152:155], v138 offset:2048
	ds_read_b128 v[180:183], v139 offset:20480
	ds_read_b128 v[184:187], v139 offset:22528
	ds_read_b128 v[156:159], v138 offset:4096
	ds_read_b128 v[168:171], v138 offset:6144
	s_waitcnt lgkmcnt(8)
	v_mfma_f32_16x16x32_bf16 v[62:65], v[66:69], v[82:85], v[62:65]
	v_mfma_f32_16x16x32_bf16 v[58:61], v[66:69], v[86:89], v[58:61]
	v_mfma_f32_16x16x32_bf16 v[54:57], v[66:69], v[90:93], v[54:57]
	v_mfma_f32_16x16x32_bf16 v[50:53], v[66:69], v[94:97], v[50:53]
	v_mfma_f32_16x16x32_bf16 v[46:49], v[70:73], v[82:85], v[46:49]
	v_mfma_f32_16x16x32_bf16 v[38:41], v[70:73], v[86:89], v[38:41]
	v_mfma_f32_16x16x32_bf16 v[34:37], v[70:73], v[90:93], v[34:37]
	v_mfma_f32_16x16x32_bf16 v[30:33], v[70:73], v[94:97], v[30:33]
	v_mfma_f32_16x16x32_bf16 v[26:29], v[74:77], v[82:85], v[26:29]
	v_mfma_f32_16x16x32_bf16 v[22:25], v[74:77], v[86:89], v[22:25]
	v_mfma_f32_16x16x32_bf16 v[18:21], v[74:77], v[90:93], v[18:21]
	v_mfma_f32_16x16x32_bf16 v[14:17], v[74:77], v[94:97], v[14:17]
	v_mfma_f32_16x16x32_bf16 v[10:13], v[78:81], v[82:85], v[10:13]
	v_mfma_f32_16x16x32_bf16 v[6:9], v[78:81], v[86:89], v[6:9]
	v_mfma_f32_16x16x32_bf16 v[2:5], v[78:81], v[90:93], v[2:5]
	v_mfma_f32_16x16x32_bf16 v[42:45], v[78:81], v[94:97], v[42:45]
	s_waitcnt lgkmcnt(0)
	v_mfma_f32_16x16x32_bf16 v[62:65], v[148:151], v[172:175], v[62:65]
	v_mfma_f32_16x16x32_bf16 v[58:61], v[148:151], v[176:179], v[58:61]
	v_mfma_f32_16x16x32_bf16 v[54:57], v[148:151], v[180:183], v[54:57]
	v_mfma_f32_16x16x32_bf16 v[50:53], v[148:151], v[184:187], v[50:53]
	v_mfma_f32_16x16x32_bf16 v[46:49], v[152:155], v[172:175], v[46:49]
	v_mfma_f32_16x16x32_bf16 v[38:41], v[152:155], v[176:179], v[38:41]
	v_mfma_f32_16x16x32_bf16 v[34:37], v[152:155], v[180:183], v[34:37]
	v_mfma_f32_16x16x32_bf16 v[30:33], v[152:155], v[184:187], v[30:33]
	s_waitcnt vmcnt(0)
	s_barrier
	ds_read_b128 v[66:69], v136 offset:32768
	ds_read_b128 v[82:85], v137 offset:49152
	ds_read_b128 v[86:89], v137 offset:51200
	ds_read_b128 v[70:73], v136 offset:34816
	ds_read_b128 v[90:93], v137 offset:53248
	ds_read_b128 v[94:97], v137 offset:55296
	ds_read_b128 v[74:77], v136 offset:36864
	ds_read_b128 v[78:81], v136 offset:38912
	v_mfma_f32_16x16x32_bf16 v[26:29], v[156:159], v[172:175], v[26:29]
	v_mfma_f32_16x16x32_bf16 v[22:25], v[156:159], v[176:179], v[22:25]
	v_mfma_f32_16x16x32_bf16 v[18:21], v[156:159], v[180:183], v[18:21]
	v_mfma_f32_16x16x32_bf16 v[14:17], v[156:159], v[184:187], v[14:17]
	v_mfma_f32_16x16x32_bf16 v[10:13], v[168:171], v[172:175], v[10:13]
	v_mfma_f32_16x16x32_bf16 v[6:9], v[168:171], v[176:179], v[6:9]
	v_mfma_f32_16x16x32_bf16 v[2:5], v[168:171], v[180:183], v[2:5]
	v_mfma_f32_16x16x32_bf16 v[42:45], v[168:171], v[184:187], v[42:45]
	ds_read_b128 v[148:151], v138 offset:32768
	ds_read_b128 v[172:175], v139 offset:49152
	ds_read_b128 v[176:179], v139 offset:51200
	ds_read_b128 v[152:155], v138 offset:34816
	ds_read_b128 v[180:183], v139 offset:53248
	ds_read_b128 v[184:187], v139 offset:55296
	ds_read_b128 v[156:159], v138 offset:36864
	ds_read_b128 v[168:171], v138 offset:38912
	s_waitcnt lgkmcnt(8)
	v_mfma_f32_16x16x32_bf16 v[62:65], v[66:69], v[82:85], v[62:65]
	v_mfma_f32_16x16x32_bf16 v[58:61], v[66:69], v[86:89], v[58:61]
	v_mfma_f32_16x16x32_bf16 v[54:57], v[66:69], v[90:93], v[54:57]
	v_mfma_f32_16x16x32_bf16 v[50:53], v[66:69], v[94:97], v[50:53]
	v_mfma_f32_16x16x32_bf16 v[46:49], v[70:73], v[82:85], v[46:49]
	v_mfma_f32_16x16x32_bf16 v[38:41], v[70:73], v[86:89], v[38:41]
	v_mfma_f32_16x16x32_bf16 v[34:37], v[70:73], v[90:93], v[34:37]
	v_mfma_f32_16x16x32_bf16 v[30:33], v[70:73], v[94:97], v[30:33]
	v_mfma_f32_16x16x32_bf16 v[26:29], v[74:77], v[82:85], v[26:29]
	v_mfma_f32_16x16x32_bf16 v[22:25], v[74:77], v[86:89], v[22:25]
	v_mfma_f32_16x16x32_bf16 v[18:21], v[74:77], v[90:93], v[18:21]
	v_mfma_f32_16x16x32_bf16 v[14:17], v[74:77], v[94:97], v[14:17]
	v_mfma_f32_16x16x32_bf16 v[10:13], v[78:81], v[82:85], v[10:13]
	v_mfma_f32_16x16x32_bf16 v[6:9], v[78:81], v[86:89], v[6:9]
	v_mfma_f32_16x16x32_bf16 v[2:5], v[78:81], v[90:93], v[2:5]
	v_mfma_f32_16x16x32_bf16 v[42:45], v[78:81], v[94:97], v[42:45]
	s_waitcnt lgkmcnt(0)
	s_barrier
	v_mfma_f32_16x16x32_bf16 v[62:65], v[148:151], v[172:175], v[62:65]
	v_mfma_f32_16x16x32_bf16 v[58:61], v[148:151], v[176:179], v[58:61]
	v_mfma_f32_16x16x32_bf16 v[54:57], v[148:151], v[180:183], v[54:57]
	v_mfma_f32_16x16x32_bf16 v[50:53], v[148:151], v[184:187], v[50:53]
	v_mfma_f32_16x16x32_bf16 v[46:49], v[152:155], v[172:175], v[46:49]
	v_mfma_f32_16x16x32_bf16 v[38:41], v[152:155], v[176:179], v[38:41]
	v_mfma_f32_16x16x32_bf16 v[34:37], v[152:155], v[180:183], v[34:37]
	v_mfma_f32_16x16x32_bf16 v[30:33], v[152:155], v[184:187], v[30:33]
	v_mfma_f32_16x16x32_bf16 v[26:29], v[156:159], v[172:175], v[26:29]
	v_mfma_f32_16x16x32_bf16 v[22:25], v[156:159], v[176:179], v[22:25]
	v_mfma_f32_16x16x32_bf16 v[18:21], v[156:159], v[180:183], v[18:21]
	v_mfma_f32_16x16x32_bf16 v[14:17], v[156:159], v[184:187], v[14:17]
	v_mfma_f32_16x16x32_bf16 v[10:13], v[168:171], v[172:175], v[10:13]
	v_mfma_f32_16x16x32_bf16 v[6:9], v[168:171], v[176:179], v[6:9]
	v_mfma_f32_16x16x32_bf16 v[2:5], v[168:171], v[180:183], v[2:5]
	v_mfma_f32_16x16x32_bf16 v[42:45], v[168:171], v[184:187], v[42:45]

.LBB0_882:
	s_mov_b64 s[14:15], 0x80
	v_lshl_add_u64 v[114:115], v[70:71], 0, s[14:15]
	v_mov_b32_e32 v38, 0
	s_mov_b32 s7, s6
	v_lshl_add_u64 v[116:117], v[114:115], 0, v[98:99]
	v_lshl_add_u64 v[118:119], v[114:115], 0, v[100:101]
	v_lshl_add_u64 v[120:121], v[114:115], 0, v[102:103]
	s_mov_b64 s[4:5], 0
	s_mov_b32 s6, 0
	v_readfirstlane_b32 s60, v104
	v_readfirstlane_b32 s61, v105
	v_readfirstlane_b32 s62, v114
	v_readfirstlane_b32 s63, v115
	v_readfirstlane_b32 s64, v122
	v_subrev_u32_e32 v140, s60, v104
	v_subrev_u32_e32 v144, s62, v114
	v_subrev_u32_e32 v145, s62, v116
	v_subrev_u32_e32 v146, s62, v118
	v_subrev_u32_e32 v147, s62, v120
	v_add_u32_e32 v141, 0x10000, v140
	v_add_u32_e32 v142, 0x20000, v140
	v_add_u32_e32 v143, 0x30000, v140
	v_add3_u32 v136, v131, v132, v133
	v_add3_u32 v137, v131, v134, v133
	v_add3_u32 v138, v130, v132, v133
	v_add3_u32 v139, v130, v134, v133
	s_add_u32 s60, s60, 0x80
	s_addc_u32 s61, s61, 0
	s_add_u32 m0, s64, 0x8000
	v_mov_b32_e32 v39, v38
	global_load_lds_dwordx4 v140, s[60:61]
	v_mov_b32_e32 v40, v38
	v_mov_b32_e32 v41, v38
	v_mov_b32_e32 v2, v38
	s_add_u32 m0, s64, 0x9000
	v_mov_b32_e32 v3, v38
	global_load_lds_dwordx4 v141, s[60:61]
	v_mov_b32_e32 v4, v38
	v_mov_b32_e32 v5, v38
	v_mov_b32_e32 v6, v38
	s_add_u32 m0, s64, 0xa000
	v_mov_b32_e32 v7, v38
	global_load_lds_dwordx4 v142, s[60:61]
	v_mov_b32_e32 v8, v38
	v_mov_b32_e32 v9, v38
	v_mov_b32_e32 v10, v38
	s_add_u32 m0, s64, 0xb000
	v_mov_b32_e32 v11, v38
	global_load_lds_dwordx4 v143, s[60:61]
	v_mov_b32_e32 v12, v38
	v_mov_b32_e32 v13, v38
	v_mov_b32_e32 v14, v38
	s_add_u32 m0, s64, 0xc000
	v_mov_b32_e32 v15, v38
	global_load_lds_dwordx4 v144, s[62:63]
	v_mov_b32_e32 v16, v38
	v_mov_b32_e32 v17, v38
	v_mov_b32_e32 v18, v38
	s_add_u32 m0, s64, 0xd000
	v_mov_b32_e32 v19, v38
	global_load_lds_dwordx4 v145, s[62:63]
	v_mov_b32_e32 v20, v38
	v_mov_b32_e32 v21, v38
	v_mov_b32_e32 v22, v38
	s_add_u32 m0, s64, 0xe000
	v_mov_b32_e32 v23, v38
	global_load_lds_dwordx4 v146, s[62:63]
	v_mov_b32_e32 v24, v38
	v_mov_b32_e32 v25, v38
	v_mov_b32_e32 v26, v38
	s_add_u32 m0, s64, 0xf000
	v_mov_b32_e32 v27, v38
	global_load_lds_dwordx4 v147, s[62:63]
	v_mov_b32_e32 v28, v38
	v_mov_b32_e32 v29, v38
	v_mov_b32_e32 v30, v38
	v_mov_b32_e32 v31, v38
	v_mov_b32_e32 v32, v38
	v_mov_b32_e32 v33, v38
	v_mov_b32_e32 v34, v38
	v_mov_b32_e32 v35, v38
	v_mov_b32_e32 v36, v38
	v_mov_b32_e32 v37, v38
	v_mov_b32_e32 v42, v38
	v_mov_b32_e32 v43, v38
	v_mov_b32_e32 v44, v38
	v_mov_b32_e32 v45, v38
	v_mov_b32_e32 v46, v38
	v_mov_b32_e32 v47, v38
	v_mov_b32_e32 v48, v38
	v_mov_b32_e32 v49, v38
	v_mov_b32_e32 v50, v38
	v_mov_b32_e32 v51, v38
	v_mov_b32_e32 v52, v38
	v_mov_b32_e32 v53, v38
	v_mov_b32_e32 v54, v38
	v_mov_b32_e32 v55, v38
	v_mov_b32_e32 v56, v38
	v_mov_b32_e32 v57, v38
	v_mov_b32_e32 v58, v38
	v_mov_b32_e32 v59, v38
	v_mov_b32_e32 v60, v38
	v_mov_b32_e32 v61, v38
	v_mov_b32_e32 v62, v38
	v_mov_b32_e32 v63, v38
	v_mov_b32_e32 v64, v38
	v_mov_b32_e32 v65, v38
	s_add_u32 s60, s60, 0x80
	s_addc_u32 s61, s61, 0
	s_add_u32 s62, s62, 0x80
	s_addc_u32 s63, s63, 0
	s_mov_b64 s[22:23], 0x10000
	s_mov_b64 s[24:25], 0x20000
	s_mov_b64 s[26:27], 0x30000
	s_mov_b64 s[16:17], 0x10080
	s_mov_b64 s[18:19], 0x20080
	s_mov_b64 s[20:21], 0x30080
	s_waitcnt vmcnt(8) lgkmcnt(0)
	s_barrier
	ds_read_b128 v[66:69], v136 offset:0
	ds_read_b128 v[82:85], v137 offset:16384
	ds_read_b128 v[86:89], v137 offset:18432
	ds_read_b128 v[70:73], v136 offset:2048
	ds_read_b128 v[90:93], v137 offset:20480
	ds_read_b128 v[94:97], v137 offset:22528
	ds_read_b128 v[74:77], v136 offset:4096
	ds_read_b128 v[78:81], v136 offset:6144
	s_mov_b32 s65, 7
.Lwout_loop:
	ds_read_b128 v[148:151], v138 offset:0
	ds_read_b128 v[172:175], v139 offset:16384
	ds_read_b128 v[176:179], v139 offset:18432
	ds_read_b128 v[152:155], v138 offset:2048
	ds_read_b128 v[180:183], v139 offset:20480
	ds_read_b128 v[184:187], v139 offset:22528
	ds_read_b128 v[156:159], v138 offset:4096
	ds_read_b128 v[168:171], v138 offset:6144
	s_waitcnt lgkmcnt(8)
	v_mfma_f32_16x16x32_bf16 v[62:65], v[66:69], v[82:85], v[62:65]
	v_mfma_f32_16x16x32_bf16 v[58:61], v[66:69], v[86:89], v[58:61]
	v_mfma_f32_16x16x32_bf16 v[54:57], v[66:69], v[90:93], v[54:57]
	v_mfma_f32_16x16x32_bf16 v[50:53], v[66:69], v[94:97], v[50:53]
	v_mfma_f32_16x16x32_bf16 v[46:49], v[70:73], v[82:85], v[46:49]
	v_mfma_f32_16x16x32_bf16 v[42:45], v[70:73], v[86:89], v[42:45]
	v_mfma_f32_16x16x32_bf16 v[34:37], v[70:73], v[90:93], v[34:37]
	v_mfma_f32_16x16x32_bf16 v[30:33], v[70:73], v[94:97], v[30:33]
	v_mfma_f32_16x16x32_bf16 v[26:29], v[74:77], v[82:85], v[26:29]
	v_mfma_f32_16x16x32_bf16 v[22:25], v[74:77], v[86:89], v[22:25]
	v_mfma_f32_16x16x32_bf16 v[18:21], v[74:77], v[90:93], v[18:21]
	v_mfma_f32_16x16x32_bf16 v[14:17], v[74:77], v[94:97], v[14:17]
	v_mfma_f32_16x16x32_bf16 v[10:13], v[78:81], v[82:85], v[10:13]
	v_mfma_f32_16x16x32_bf16 v[6:9], v[78:81], v[86:89], v[6:9]
	v_mfma_f32_16x16x32_bf16 v[2:5], v[78:81], v[90:93], v[2:5]
	v_mfma_f32_16x16x32_bf16 v[38:41], v[78:81], v[94:97], v[38:41]
	s_waitcnt lgkmcnt(0)
	s_barrier
	s_add_u32 m0, s64, 0x0
	v_mfma_f32_16x16x32_bf16 v[62:65], v[148:151], v[172:175], v[62:65]
	global_load_lds_dwordx4 v140, s[60:61]
	s_add_u32 m0, s64, 0x1000
	v_mfma_f32_16x16x32_bf16 v[58:61], v[148:151], v[176:179], v[58:61]
	global_load_lds_dwordx4 v141, s[60:61]
	s_add_u32 m0, s64, 0x2000
	v_mfma_f32_16x16x32_bf16 v[54:57], v[148:151], v[180:183], v[54:57]
	global_load_lds_dwordx4 v142, s[60:61]
	s_add_u32 m0, s64, 0x3000
	v_mfma_f32_16x16x32_bf16 v[50:53], v[148:151], v[184:187], v[50:53]
	global_load_lds_dwordx4 v143, s[60:61]
	s_add_u32 m0, s64, 0x4000
	v_mfma_f32_16x16x32_bf16 v[46:49], v[152:155], v[172:175], v[46:49]
	global_load_lds_dwordx4 v144, s[62:63]
	s_add_u32 m0, s64, 0x5000
	v_mfma_f32_16x16x32_bf16 v[42:45], v[152:155], v[176:179], v[42:45]
	global_load_lds_dwordx4 v145, s[62:63]
	s_add_u32 m0, s64, 0x6000
	v_mfma_f32_16x16x32_bf16 v[34:37], v[152:155], v[180:183], v[34:37]
	global_load_lds_dwordx4 v146, s[62:63]
	s_add_u32 m0, s64, 0x7000
	v_mfma_f32_16x16x32_bf16 v[30:33], v[152:155], v[184:187], v[30:33]
	global_load_lds_dwordx4 v147, s[62:63]
	s_add_u32 s60, s60, 0x80
	s_addc_u32 s61, s61, 0
	s_add_u32 s62, s62, 0x80
	s_addc_u32 s63, s63, 0
	s_waitcnt vmcnt(8)
	s_barrier
	ds_read_b128 v[66:69], v136 offset:32768
	ds_read_b128 v[82:85], v137 offset:49152
	ds_read_b128 v[86:89], v137 offset:51200
	ds_read_b128 v[70:73], v136 offset:34816
	ds_read_b128 v[90:93], v137 offset:53248
	ds_read_b128 v[94:97], v137 offset:55296
	ds_read_b128 v[74:77], v136 offset:36864
	ds_read_b128 v[78:81], v136 offset:38912
	v_mfma_f32_16x16x32_bf16 v[26:29], v[156:159], v[172:175], v[26:29]
	v_mfma_f32_16x16x32_bf16 v[22:25], v[156:159], v[176:179], v[22:25]
	v_mfma_f32_16x16x32_bf16 v[18:21], v[156:159], v[180:183], v[18:21]
	v_mfma_f32_16x16x32_bf16 v[14:17], v[156:159], v[184:187], v[14:17]
	v_mfma_f32_16x16x32_bf16 v[10:13], v[168:171], v[172:175], v[10:13]
	v_mfma_f32_16x16x32_bf16 v[6:9], v[168:171], v[176:179], v[6:9]
	v_mfma_f32_16x16x32_bf16 v[2:5], v[168:171], v[180:183], v[2:5]
	v_mfma_f32_16x16x32_bf16 v[38:41], v[168:171], v[184:187], v[38:41]
	ds_read_b128 v[148:151], v138 offset:32768
	ds_read_b128 v[172:175], v139 offset:49152
	ds_read_b128 v[176:179], v139 offset:51200
	ds_read_b128 v[152:155], v138 offset:34816
	ds_read_b128 v[180:183], v139 offset:53248
	ds_read_b128 v[184:187], v139 offset:55296
	ds_read_b128 v[156:159], v138 offset:36864
	ds_read_b128 v[168:171], v138 offset:38912
	s_waitcnt lgkmcnt(8)
	v_mfma_f32_16x16x32_bf16 v[62:65], v[66:69], v[82:85], v[62:65]
	v_mfma_f32_16x16x32_bf16 v[58:61], v[66:69], v[86:89], v[58:61]
	v_mfma_f32_16x16x32_bf16 v[54:57], v[66:69], v[90:93], v[54:57]
	v_mfma_f32_16x16x32_bf16 v[50:53], v[66:69], v[94:97], v[50:53]
	v_mfma_f32_16x16x32_bf16 v[46:49], v[70:73], v[82:85], v[46:49]
	v_mfma_f32_16x16x32_bf16 v[42:45], v[70:73], v[86:89], v[42:45]
	v_mfma_f32_16x16x32_bf16 v[34:37], v[70:73], v[90:93], v[34:37]
	v_mfma_f32_16x16x32_bf16 v[30:33], v[70:73], v[94:97], v[30:33]
	v_mfma_f32_16x16x32_bf16 v[26:29], v[74:77], v[82:85], v[26:29]
	v_mfma_f32_16x16x32_bf16 v[22:25], v[74:77], v[86:89], v[22:25]
	v_mfma_f32_16x16x32_bf16 v[18:21], v[74:77], v[90:93], v[18:21]
	v_mfma_f32_16x16x32_bf16 v[14:17], v[74:77], v[94:97], v[14:17]
	v_mfma_f32_16x16x32_bf16 v[10:13], v[78:81], v[82:85], v[10:13]
	v_mfma_f32_16x16x32_bf16 v[6:9], v[78:81], v[86:89], v[6:9]
	v_mfma_f32_16x16x32_bf16 v[2:5], v[78:81], v[90:93], v[2:5]
	v_mfma_f32_16x16x32_bf16 v[38:41], v[78:81], v[94:97], v[38:41]
	s_waitcnt lgkmcnt(0)
	s_barrier
	s_add_u32 m0, s64, 0x8000
	v_mfma_f32_16x16x32_bf16 v[62:65], v[148:151], v[172:175], v[62:65]
	global_load_lds_dwordx4 v140, s[60:61]
	s_add_u32 m0, s64, 0x9000
	v_mfma_f32_16x16x32_bf16 v[58:61], v[148:151], v[176:179], v[58:61]
	global_load_lds_dwordx4 v141, s[60:61]
	s_add_u32 m0, s64, 0xa000
	v_mfma_f32_16x16x32_bf16 v[54:57], v[148:151], v[180:183], v[54:57]
	global_load_lds_dwordx4 v142, s[60:61]
	s_add_u32 m0, s64, 0xb000
	v_mfma_f32_16x16x32_bf16 v[50:53], v[148:151], v[184:187], v[50:53]
	global_load_lds_dwordx4 v143, s[60:61]
	s_add_u32 m0, s64, 0xc000
	v_mfma_f32_16x16x32_bf16 v[46:49], v[152:155], v[172:175], v[46:49]
	global_load_lds_dwordx4 v144, s[62:63]
	s_add_u32 m0, s64, 0xd000
	v_mfma_f32_16x16x32_bf16 v[42:45], v[152:155], v[176:179], v[42:45]
	global_load_lds_dwordx4 v145, s[62:63]
	s_add_u32 m0, s64, 0xe000
	v_mfma_f32_16x16x32_bf16 v[34:37], v[152:155], v[180:183], v[34:37]
	global_load_lds_dwordx4 v146, s[62:63]
	s_add_u32 m0, s64, 0xf000
	v_mfma_f32_16x16x32_bf16 v[30:33], v[152:155], v[184:187], v[30:33]
	global_load_lds_dwordx4 v147, s[62:63]
	s_add_u32 s60, s60, 0x80
	s_addc_u32 s61, s61, 0
	s_add_u32 s62, s62, 0x80
	s_addc_u32 s63, s63, 0
	s_waitcnt vmcnt(8)
	s_barrier
	ds_read_b128 v[66:69], v136 offset:0
	ds_read_b128 v[82:85], v137 offset:16384
	ds_read_b128 v[86:89], v137 offset:18432
	ds_read_b128 v[70:73], v136 offset:2048
	ds_read_b128 v[90:93], v137 offset:20480
	ds_read_b128 v[94:97], v137 offset:22528
	ds_read_b128 v[74:77], v136 offset:4096
	ds_read_b128 v[78:81], v136 offset:6144
	v_mfma_f32_16x16x32_bf16 v[26:29], v[156:159], v[172:175], v[26:29]
	v_mfma_f32_16x16x32_bf16 v[22:25], v[156:159], v[176:179], v[22:25]
	v_mfma_f32_16x16x32_bf16 v[18:21], v[156:159], v[180:183], v[18:21]
	v_mfma_f32_16x16x32_bf16 v[14:17], v[156:159], v[184:187], v[14:17]
	v_mfma_f32_16x16x32_bf16 v[10:13], v[168:171], v[172:175], v[10:13]
	v_mfma_f32_16x16x32_bf16 v[6:9], v[168:171], v[176:179], v[6:9]
	v_mfma_f32_16x16x32_bf16 v[2:5], v[168:171], v[180:183], v[2:5]
	v_mfma_f32_16x16x32_bf16 v[38:41], v[168:171], v[184:187], v[38:41]
	s_sub_i32 s65, s65, 1
	s_cmp_lg_u32 s65, 0
	s_cbranch_scc1 .Lwout_loop
	ds_read_b128 v[148:151], v138 offset:0
	ds_read_b128 v[172:175], v139 offset:16384
	ds_read_b128 v[176:179], v139 offset:18432
	ds_read_b128 v[152:155], v138 offset:2048
	ds_read_b128 v[180:183], v139 offset:20480
	ds_read_b128 v[184:187], v139 offset:22528
	ds_read_b128 v[156:159], v138 offset:4096
	ds_read_b128 v[168:171], v138 offset:6144
	s_waitcnt lgkmcnt(8)
	v_mfma_f32_16x16x32_bf16 v[62:65], v[66:69], v[82:85], v[62:65]
	v_mfma_f32_16x16x32_bf16 v[58:61], v[66:69], v[86:89], v[58:61]
	v_mfma_f32_16x16x32_bf16 v[54:57], v[66:69], v[90:93], v[54:57]
	v_mfma_f32_16x16x32_bf16 v[50:53], v[66:69], v[94:97], v[50:53]
	v_mfma_f32_16x16x32_bf16 v[46:49], v[70:73], v[82:85], v[46:49]
	v_mfma_f32_16x16x32_bf16 v[42:45], v[70:73], v[86:89], v[42:45]
	v_mfma_f32_16x16x32_bf16 v[34:37], v[70:73], v[90:93], v[34:37]
	v_mfma_f32_16x16x32_bf16 v[30:33], v[70:73], v[94:97], v[30:33]
	v_mfma_f32_16x16x32_bf16 v[26:29], v[74:77], v[82:85], v[26:29]
	v_mfma_f32_16x16x32_bf16 v[22:25], v[74:77], v[86:89], v[22:25]
	v_mfma_f32_16x16x32_bf16 v[18:21], v[74:77], v[90:93], v[18:21]
	v_mfma_f32_16x16x32_bf16 v[14:17], v[74:77], v[94:97], v[14:17]
	v_mfma_f32_16x16x32_bf16 v[10:13], v[78:81], v[82:85], v[10:13]
	v_mfma_f32_16x16x32_bf16 v[6:9], v[78:81], v[86:89], v[6:9]
	v_mfma_f32_16x16x32_bf16 v[2:5], v[78:81], v[90:93], v[2:5]
	v_mfma_f32_16x16x32_bf16 v[38:41], v[78:81], v[94:97], v[38:41]
	s_waitcnt lgkmcnt(0)
	v_mfma_f32_16x16x32_bf16 v[62:65], v[148:151], v[172:175], v[62:65]
	v_mfma_f32_16x16x32_bf16 v[58:61], v[148:151], v[176:179], v[58:61]
	v_mfma_f32_16x16x32_bf16 v[54:57], v[148:151], v[180:183], v[54:57]
	v_mfma_f32_16x16x32_bf16 v[50:53], v[148:151], v[184:187], v[50:53]
	v_mfma_f32_16x16x32_bf16 v[46:49], v[152:155], v[172:175], v[46:49]
	v_mfma_f32_16x16x32_bf16 v[42:45], v[152:155], v[176:179], v[42:45]
	v_mfma_f32_16x16x32_bf16 v[34:37], v[152:155], v[180:183], v[34:37]
	v_mfma_f32_16x16x32_bf16 v[30:33], v[152:155], v[184:187], v[30:33]
	s_waitcnt vmcnt(0)
	s_barrier
	ds_read_b128 v[66:69], v136 offset:32768
	ds_read_b128 v[82:85], v137 offset:49152
	ds_read_b128 v[86:89], v137 offset:51200
	ds_read_b128 v[70:73], v136 offset:34816
	ds_read_b128 v[90:93], v137 offset:53248
	ds_read_b128 v[94:97], v137 offset:55296
	ds_read_b128 v[74:77], v136 offset:36864
	ds_read_b128 v[78:81], v136 offset:38912
	v_mfma_f32_16x16x32_bf16 v[26:29], v[156:159], v[172:175], v[26:29]
	v_mfma_f32_16x16x32_bf16 v[22:25], v[156:159], v[176:179], v[22:25]
	v_mfma_f32_16x16x32_bf16 v[18:21], v[156:159], v[180:183], v[18:21]
	v_mfma_f32_16x16x32_bf16 v[14:17], v[156:159], v[184:187], v[14:17]
	v_mfma_f32_16x16x32_bf16 v[10:13], v[168:171], v[172:175], v[10:13]
	v_mfma_f32_16x16x32_bf16 v[6:9], v[168:171], v[176:179], v[6:9]
	v_mfma_f32_16x16x32_bf16 v[2:5], v[168:171], v[180:183], v[2:5]
	v_mfma_f32_16x16x32_bf16 v[38:41], v[168:171], v[184:187], v[38:41]
	ds_read_b128 v[148:151], v138 offset:32768
	ds_read_b128 v[172:175], v139 offset:49152
	ds_read_b128 v[176:179], v139 offset:51200
	ds_read_b128 v[152:155], v138 offset:34816
	ds_read_b128 v[180:183], v139 offset:53248
	ds_read_b128 v[184:187], v139 offset:55296
	ds_read_b128 v[156:159], v138 offset:36864
	ds_read_b128 v[168:171], v138 offset:38912
	s_waitcnt lgkmcnt(8)
	v_mfma_f32_16x16x32_bf16 v[62:65], v[66:69], v[82:85], v[62:65]
	v_mfma_f32_16x16x32_bf16 v[58:61], v[66:69], v[86:89], v[58:61]
	v_mfma_f32_16x16x32_bf16 v[54:57], v[66:69], v[90:93], v[54:57]
	v_mfma_f32_16x16x32_bf16 v[50:53], v[66:69], v[94:97], v[50:53]
	v_mfma_f32_16x16x32_bf16 v[46:49], v[70:73], v[82:85], v[46:49]
	v_mfma_f32_16x16x32_bf16 v[42:45], v[70:73], v[86:89], v[42:45]
	v_mfma_f32_16x16x32_bf16 v[34:37], v[70:73], v[90:93], v[34:37]
	v_mfma_f32_16x16x32_bf16 v[30:33], v[70:73], v[94:97], v[30:33]
	v_mfma_f32_16x16x32_bf16 v[26:29], v[74:77], v[82:85], v[26:29]
	v_mfma_f32_16x16x32_bf16 v[22:25], v[74:77], v[86:89], v[22:25]
	v_mfma_f32_16x16x32_bf16 v[18:21], v[74:77], v[90:93], v[18:21]
	v_mfma_f32_16x16x32_bf16 v[14:17], v[74:77], v[94:97], v[14:17]
	v_mfma_f32_16x16x32_bf16 v[10:13], v[78:81], v[82:85], v[10:13]
	v_mfma_f32_16x16x32_bf16 v[6:9], v[78:81], v[86:89], v[6:9]
	v_mfma_f32_16x16x32_bf16 v[2:5], v[78:81], v[90:93], v[2:5]
	v_mfma_f32_16x16x32_bf16 v[38:41], v[78:81], v[94:97], v[38:41]
	s_waitcnt lgkmcnt(0)
	s_barrier
	v_mfma_f32_16x16x32_bf16 v[62:65], v[148:151], v[172:175], v[62:65]
	v_mfma_f32_16x16x32_bf16 v[58:61], v[148:151], v[176:179], v[58:61]
	v_mfma_f32_16x16x32_bf16 v[54:57], v[148:151], v[180:183], v[54:57]
	v_mfma_f32_16x16x32_bf16 v[50:53], v[148:151], v[184:187], v[50:53]
	v_mfma_f32_16x16x32_bf16 v[46:49], v[152:155], v[172:175], v[46:49]
	v_mfma_f32_16x16x32_bf16 v[42:45], v[152:155], v[176:179], v[42:45]
	v_mfma_f32_16x16x32_bf16 v[34:37], v[152:155], v[180:183], v[34:37]
	v_mfma_f32_16x16x32_bf16 v[30:33], v[152:155], v[184:187], v[30:33]
	v_mfma_f32_16x16x32_bf16 v[26:29], v[156:159], v[172:175], v[26:29]
	v_mfma_f32_16x16x32_bf16 v[22:25], v[156:159], v[176:179], v[22:25]
	v_mfma_f32_16x16x32_bf16 v[18:21], v[156:159], v[180:183], v[18:21]
	v_mfma_f32_16x16x32_bf16 v[14:17], v[156:159], v[184:187], v[14:17]
	v_mfma_f32_16x16x32_bf16 v[10:13], v[168:171], v[172:175], v[10:13]
	v_mfma_f32_16x16x32_bf16 v[6:9], v[168:171], v[176:179], v[6:9]
	v_mfma_f32_16x16x32_bf16 v[2:5], v[168:171], v[180:183], v[2:5]
	v_mfma_f32_16x16x32_bf16 v[38:41], v[168:171], v[184:187], v[38:41]
.LBB0_886:
	ds_write2_b32 v135, v62, v58 offset1:16
	ds_write2_b32 v135, v63, v59 offset0:132 offset1:148
	v_add_u32_e32 v58, 0x400, v135
	ds_write2_b32 v58, v64, v60 offset0:8 offset1:24
	ds_write2_b32 v58, v65, v61 offset0:140 offset1:156
	ds_write2_b32 v135, v54, v50 offset0:32 offset1:48
	ds_write2_b32 v135, v55, v51 offset0:164 offset1:180
	ds_write2_b32 v58, v56, v52 offset0:40 offset1:56
	ds_write2_b32 v58, v57, v53 offset0:172 offset1:188
	v_add_u32_e32 v50, 0x2000, v135
	ds_write2_b32 v50, v46, v42 offset0:64 offset1:80
	ds_write2_b32 v50, v47, v43 offset0:196 offset1:212
	v_add_u32_e32 v42, 0x2400, v135
	ds_write2_b32 v42, v48, v44 offset0:72 offset1:88
	ds_write2_b32 v42, v49, v45 offset0:204 offset1:220
	ds_write2_b32 v50, v34, v30 offset0:96 offset1:112
	ds_write2_b32 v50, v35, v31 offset0:228 offset1:244
	ds_write2_b32 v42, v36, v32 offset0:104 offset1:120
	ds_write2_b32 v42, v37, v33 offset0:236 offset1:252
	v_add_u32_e32 v30, 0x4000, v135
	ds_write2_b32 v30, v26, v22 offset0:128 offset1:144
	v_add_u32_e32 v22, 0x4400, v135
	ds_write2_b32 v22, v27, v23 offset0:4 offset1:20
	ds_write2_b32 v22, v28, v24 offset0:136 offset1:152
	v_add_u32_e32 v23, 0x4800, v135
	ds_write2_b32 v23, v29, v25 offset0:12 offset1:28
	ds_write2_b32 v30, v18, v14 offset0:160 offset1:176
	ds_write2_b32 v22, v19, v15 offset0:36 offset1:52
	ds_write2_b32 v22, v20, v16 offset0:168 offset1:184
	ds_write2_b32 v23, v21, v17 offset0:44 offset1:60
	v_add_u32_e32 v14, 0x6000, v135
	ds_write2_b32 v14, v10, v6 offset0:192 offset1:208
	v_add_u32_e32 v6, 0x6400, v135
	ds_write2_b32 v6, v11, v7 offset0:68 offset1:84
	ds_write2_b32 v6, v12, v8 offset0:200 offset1:216
	v_add_u32_e32 v7, 0x6800, v135
	ds_write2_b32 v7, v13, v9 offset0:76 offset1:92
	ds_write2_b32 v14, v2, v38 offset0:224 offset1:240
	ds_write2_b32 v6, v3, v39 offset0:100 offset1:116
	ds_write2_b32 v6, v4, v40 offset0:232 offset1:248
	ds_write2_b32 v7, v5, v41 offset0:108 offset1:124
	v_mov_b32_e32 v2, v193
	s_waitcnt lgkmcnt(0)
	s_barrier
	s_movk_i32 s4, 0x210
	v_ashrrev_i32_e32 v3, 5, v2
	v_lshlrev_b32_e32 v2, 4, v2
	v_and_b32_e32 v2, 0x1f0, v2
	v_mul_lo_u32 v3, v3, s4
	v_add3_u32 v2, 0, v2, v3
	ds_read_b128 v[66:69], v2
	ds_read_b128 v[58:61], v2 offset:4224
	ds_read_b128 v[54:57], v2 offset:8448
	ds_read_b128 v[50:53], v2 offset:12672
	ds_read_b128 v[46:49], v2 offset:16896
	ds_read_b128 v[42:45], v2 offset:21120
	ds_read_b128 v[38:41], v2 offset:25344
	ds_read_b128 v[34:37], v2 offset:29568
	ds_read_b128 v[30:33], v2 offset:33792
	ds_read_b128 v[26:29], v2 offset:38016
	ds_read_b128 v[22:25], v2 offset:42240
	ds_read_b128 v[18:21], v2 offset:46464
	ds_read_b128 v[14:17], v2 offset:50688
	ds_read_b128 v[10:13], v2 offset:54912
	ds_read_b128 v[6:9], v2 offset:59136
	ds_read_b128 v[2:5], v2 offset:63360
	s_add_i32 s6, s7, s50
	s_cmp_ge_i32 s6, s2
	s_cselect_b64 s[4:5], -1, 0
	s_cmp_lt_i32 s6, s2
	s_waitcnt lgkmcnt(0)
	s_barrier
	s_cbranch_scc1 .LBB0_880
	s_movk_i32 s12, 0xff80
	s_mov_b32 s13, -1
	v_lshl_add_u64 v[70:71], v[114:115], 0, s[12:13]
	s_branch .LBB0_881
